# sc1 on SwiGLU ACT stores and final-norm output stores
# baseline (speedup 1.0000x reference)
.LBB0_961:
	s_or_b64 exec, exec, s[18:19]
	s_waitcnt vmcnt(12)
	ds_bpermute_b32 v65, v54, v64
	s_lshl_b64 s[16:17], s[2:3], 12
	s_waitcnt lgkmcnt(0)
	v_add_f32_e32 v64, v64, v65
	ds_bpermute_b32 v65, v55, v64
	s_waitcnt lgkmcnt(0)
	v_add_f32_e32 v64, v64, v65
	ds_bpermute_b32 v65, v56, v64
	s_waitcnt lgkmcnt(0)
	v_add_f32_e32 v65, v64, v65
	ds_bpermute_b32 v66, v57, v65
	v_lshlrev_b32_e32 v64, 16, v52
	s_waitcnt lgkmcnt(0)
	v_add_f32_e32 v65, v65, v66
	ds_bpermute_b32 v67, v58, v65
	v_and_b32_e32 v65, 0xffff0000, v52
	v_lshlrev_b32_e32 v52, 16, v53
	v_and_b32_e32 v53, 0xffff0000, v53
	v_lshlrev_b32_e32 v66, 16, v50
	s_waitcnt lgkmcnt(0)
	v_fmamk_f32 v67, v67, 0x3a800000, v59
	v_mul_f32_e32 v68, 0x4f800000, v67
	v_cmp_gt_f32_e32 vcc, s21, v67
	s_nop 1
	v_cndmask_b32_e32 v68, v67, v68, vcc
	v_sqrt_f32_e32 v69, v68
	v_and_b32_e32 v67, 0xffff0000, v50
	v_lshlrev_b32_e32 v50, 16, v51
	v_and_b32_e32 v51, 0xffff0000, v51
	v_add_u32_e32 v70, -1, v69
	v_add_u32_e32 v71, 1, v69
	v_fma_f32 v72, -v70, v69, v68
	v_fma_f32 v73, -v71, v69, v68
	v_cmp_ge_f32_e64 s[2:3], 0, v72
	s_nop 1
	v_cndmask_b32_e64 v69, v69, v70, s[2:3]
	v_cmp_lt_f32_e64 s[2:3], 0, v73
	s_nop 1
	v_cndmask_b32_e64 v69, v69, v71, s[2:3]
	v_mul_f32_e32 v70, 0x37800000, v69
	v_cndmask_b32_e32 v69, v69, v70, vcc
	v_cmp_class_f32_e32 vcc, v68, v60
	s_nop 1
	v_cndmask_b32_e32 v70, v69, v68, vcc
	v_div_scale_f32 v71, s[2:3], v70, v70, 1.0
	v_rcp_f32_e32 v72, v71
	v_div_scale_f32 v73, vcc, 1.0, v70, 1.0
	v_lshl_add_u64 v[68:69], v[20:21], 0, s[16:17]
	v_fma_f32 v74, -v71, v72, 1.0
	v_fmac_f32_e32 v72, v74, v72
	v_mul_f32_e32 v74, v73, v72
	v_fma_f32 v75, -v71, v74, v73
	v_fmac_f32_e32 v74, v75, v72
	v_fma_f32 v71, -v71, v74, v73
	v_div_fmas_f32 v71, v71, v72, v74
	v_div_fixup_f32 v70, v71, v70, 1.0
	v_pk_mul_f32 v[64:65], v[70:71], v[64:65] op_sel_hi:[0,1]
	v_pk_mul_f32 v[52:53], v[70:71], v[52:53] op_sel_hi:[0,1]
	v_pk_mul_f32 v[72:73], v[70:71], v[66:67] op_sel_hi:[0,1]
	v_pk_mul_f32 v[66:67], v[70:71], v[50:51] op_sel_hi:[0,1]
	v_pk_mul_f32 v[52:53], v[2:3], v[52:53]
	v_pk_mul_f32 v[50:51], v[0:1], v[64:65]
	v_pk_mul_f32 v[66:67], v[6:7], v[66:67]
	v_pk_mul_f32 v[64:65], v[4:5], v[72:73]
	global_store_dwordx4 v[68:69], v[50:53], off sc1
	global_store_dwordx4 v[68:69], v[64:67], off offset:1024 sc1
	s_andn2_b64 vcc, exec, s[14:15]
	v_lshlrev_b32_e32 v50, 16, v48
	v_and_b32_e32 v51, 0xffff0000, v48
	v_lshlrev_b32_e32 v48, 16, v49
	v_and_b32_e32 v49, 0xffff0000, v49
	v_pk_mul_f32 v[52:53], v[70:71], v[50:51] op_sel_hi:[0,1]
	v_pk_mul_f32 v[48:49], v[70:71], v[48:49] op_sel_hi:[0,1]
	v_pk_mul_f32 v[50:51], v[10:11], v[48:49]
	v_pk_mul_f32 v[48:49], v[8:9], v[52:53]
	global_store_dwordx4 v[68:69], v[48:51], off offset:2048 sc1
	s_nop 1
	v_lshlrev_b32_e32 v48, 16, v46
	v_and_b32_e32 v49, 0xffff0000, v46
	v_lshlrev_b32_e32 v46, 16, v47
	v_and_b32_e32 v47, 0xffff0000, v47
	v_pk_mul_f32 v[50:51], v[70:71], v[48:49] op_sel_hi:[0,1]
	v_pk_mul_f32 v[46:47], v[70:71], v[46:47] op_sel_hi:[0,1]
	v_pk_mul_f32 v[48:49], v[14:15], v[46:47]
	v_pk_mul_f32 v[46:47], v[12:13], v[50:51]
	global_store_dwordx4 v[68:69], v[46:49], off offset:3072 sc1
	s_cbranch_vccnz .LBB0_964
	s_waitcnt vmcnt(12)
	ds_bpermute_b32 v46, v54, v63
	s_ashr_i32 s5, s4, 31
	s_lshl_b64 s[14:15], s[4:5], 12
	s_waitcnt lgkmcnt(0)
	v_add_f32_e32 v46, v63, v46
	ds_bpermute_b32 v47, v55, v46
	s_waitcnt lgkmcnt(0)
	v_add_f32_e32 v46, v46, v47
	ds_bpermute_b32 v47, v56, v46
	s_waitcnt lgkmcnt(0)
	v_add_f32_e32 v48, v46, v47
	ds_bpermute_b32 v49, v57, v48
	v_lshlrev_b32_e32 v46, 16, v44
	v_and_b32_e32 v47, 0xffff0000, v44
	s_waitcnt lgkmcnt(0)
	v_add_f32_e32 v44, v48, v49
	ds_bpermute_b32 v50, v58, v44
	v_lshlrev_b32_e32 v48, 16, v42
	v_and_b32_e32 v49, 0xffff0000, v42
	v_lshlrev_b32_e32 v44, 16, v45
	v_and_b32_e32 v45, 0xffff0000, v45
	s_waitcnt lgkmcnt(0)
	v_fmamk_f32 v42, v50, 0x3a800000, v59
	v_mul_f32_e32 v50, 0x4f800000, v42
	v_cmp_gt_f32_e32 vcc, s21, v42
	s_nop 1
	v_cndmask_b32_e32 v50, v42, v50, vcc
	v_sqrt_f32_e32 v51, v50
	v_lshlrev_b32_e32 v42, 16, v43
	v_and_b32_e32 v43, 0xffff0000, v43
	v_add_u32_e32 v52, -1, v51
	v_add_u32_e32 v53, 1, v51
	v_fma_f32 v63, -v52, v51, v50
	v_fma_f32 v64, -v53, v51, v50
	v_cmp_ge_f32_e64 s[2:3], 0, v63
	s_nop 1
	v_cndmask_b32_e64 v51, v51, v52, s[2:3]
	v_cmp_lt_f32_e64 s[2:3], 0, v64
	s_nop 1
	v_cndmask_b32_e64 v51, v51, v53, s[2:3]
	v_mul_f32_e32 v52, 0x37800000, v51
	v_cndmask_b32_e32 v51, v51, v52, vcc
	v_cmp_class_f32_e32 vcc, v50, v60
	s_nop 1
	v_cndmask_b32_e32 v52, v51, v50, vcc
	v_div_scale_f32 v53, s[2:3], v52, v52, 1.0
	v_rcp_f32_e32 v63, v53
	v_div_scale_f32 v64, vcc, 1.0, v52, 1.0
	v_lshl_add_u64 v[50:51], v[20:21], 0, s[14:15]
	v_fma_f32 v65, -v53, v63, 1.0
	v_fmac_f32_e32 v63, v65, v63
	v_mul_f32_e32 v65, v64, v63
	v_fma_f32 v66, -v53, v65, v64
	v_fmac_f32_e32 v65, v66, v63
	v_fma_f32 v53, -v53, v65, v64
	v_div_fmas_f32 v53, v53, v63, v65
	v_div_fixup_f32 v52, v53, v52, 1.0
	v_pk_mul_f32 v[46:47], v[52:53], v[46:47] op_sel_hi:[0,1]
	v_pk_mul_f32 v[44:45], v[52:53], v[44:45] op_sel_hi:[0,1]
	v_pk_mul_f32 v[48:49], v[52:53], v[48:49] op_sel_hi:[0,1]
	v_pk_mul_f32 v[64:65], v[52:53], v[42:43] op_sel_hi:[0,1]
	v_pk_mul_f32 v[44:45], v[2:3], v[44:45]
	v_pk_mul_f32 v[42:43], v[0:1], v[46:47]
	v_pk_mul_f32 v[46:47], v[6:7], v[64:65]
	global_store_dwordx4 v[50:51], v[42:45], off sc1
	s_nop 1
	v_pk_mul_f32 v[44:45], v[4:5], v[48:49]
	v_lshlrev_b32_e32 v42, 16, v40
	v_and_b32_e32 v43, 0xffff0000, v40
	v_lshlrev_b32_e32 v40, 16, v41
	v_and_b32_e32 v41, 0xffff0000, v41
	global_store_dwordx4 v[50:51], v[44:47], off offset:1024 sc1
	v_pk_mul_f32 v[40:41], v[52:53], v[40:41] op_sel_hi:[0,1]
	s_nop 0
	v_pk_mul_f32 v[44:45], v[52:53], v[42:43] op_sel_hi:[0,1]
	v_pk_mul_f32 v[42:43], v[10:11], v[40:41]
	v_pk_mul_f32 v[40:41], v[8:9], v[44:45]
	global_store_dwordx4 v[50:51], v[40:43], off offset:2048 sc1
	s_nop 1
	v_lshlrev_b32_e32 v40, 16, v38
	v_and_b32_e32 v41, 0xffff0000, v38
	v_lshlrev_b32_e32 v38, 16, v39
	v_and_b32_e32 v39, 0xffff0000, v39
	v_pk_mul_f32 v[42:43], v[52:53], v[40:41] op_sel_hi:[0,1]
	v_pk_mul_f32 v[38:39], v[52:53], v[38:39] op_sel_hi:[0,1]
	v_pk_mul_f32 v[40:41], v[14:15], v[38:39]
	v_pk_mul_f32 v[38:39], v[12:13], v[42:43]
	global_store_dwordx4 v[50:51], v[38:41], off offset:3072 sc1
	s_andn2_b64 vcc, exec, s[12:13]
	s_cbranch_vccz .LBB0_965

.LBB0_965:
	s_waitcnt vmcnt(8)
	ds_bpermute_b32 v38, v54, v62
	s_ashr_i32 s11, s10, 31
	s_lshl_b64 s[10:11], s[10:11], 12
	s_waitcnt lgkmcnt(0)
	v_add_f32_e32 v38, v62, v38
	ds_bpermute_b32 v39, v55, v38
	s_waitcnt lgkmcnt(0)
	v_add_f32_e32 v38, v38, v39
	ds_bpermute_b32 v39, v56, v38
	s_waitcnt lgkmcnt(0)
	v_add_f32_e32 v40, v38, v39
	ds_bpermute_b32 v41, v57, v40
	v_lshlrev_b32_e32 v38, 16, v36
	v_and_b32_e32 v39, 0xffff0000, v36
	s_waitcnt lgkmcnt(0)
	v_add_f32_e32 v36, v40, v41
	ds_bpermute_b32 v42, v58, v36
	v_lshlrev_b32_e32 v40, 16, v34
	v_and_b32_e32 v41, 0xffff0000, v34
	v_lshlrev_b32_e32 v36, 16, v37
	v_and_b32_e32 v37, 0xffff0000, v37
	s_waitcnt lgkmcnt(0)
	v_fmamk_f32 v34, v42, 0x3a800000, v59
	v_mul_f32_e32 v42, 0x4f800000, v34
	v_cmp_gt_f32_e32 vcc, s21, v34
	s_nop 1
	v_cndmask_b32_e32 v42, v34, v42, vcc
	v_sqrt_f32_e32 v43, v42
	v_lshlrev_b32_e32 v34, 16, v35
	v_and_b32_e32 v35, 0xffff0000, v35
	v_add_u32_e32 v44, -1, v43
	v_add_u32_e32 v45, 1, v43
	v_fma_f32 v46, -v44, v43, v42
	v_fma_f32 v47, -v45, v43, v42
	v_cmp_ge_f32_e64 s[2:3], 0, v46
	s_nop 1
	v_cndmask_b32_e64 v43, v43, v44, s[2:3]
	v_cmp_lt_f32_e64 s[2:3], 0, v47
	s_nop 1
	v_cndmask_b32_e64 v43, v43, v45, s[2:3]
	v_mul_f32_e32 v44, 0x37800000, v43
	v_cndmask_b32_e32 v43, v43, v44, vcc
	v_cmp_class_f32_e32 vcc, v42, v60
	s_nop 1
	v_cndmask_b32_e32 v44, v43, v42, vcc
	v_div_scale_f32 v45, s[2:3], v44, v44, 1.0
	v_rcp_f32_e32 v46, v45
	v_div_scale_f32 v47, vcc, 1.0, v44, 1.0
	v_lshl_add_u64 v[42:43], v[20:21], 0, s[10:11]
	v_fma_f32 v48, -v45, v46, 1.0
	v_fmac_f32_e32 v46, v48, v46
	v_mul_f32_e32 v48, v47, v46
	v_fma_f32 v49, -v45, v48, v47
	v_fmac_f32_e32 v48, v49, v46
	v_fma_f32 v45, -v45, v48, v47
	v_div_fmas_f32 v45, v45, v46, v48
	v_div_fixup_f32 v44, v45, v44, 1.0
	v_pk_mul_f32 v[38:39], v[44:45], v[38:39] op_sel_hi:[0,1]
	v_pk_mul_f32 v[36:37], v[44:45], v[36:37] op_sel_hi:[0,1]
	v_pk_mul_f32 v[40:41], v[44:45], v[40:41] op_sel_hi:[0,1]
	v_pk_mul_f32 v[46:47], v[44:45], v[34:35] op_sel_hi:[0,1]
	v_pk_mul_f32 v[36:37], v[2:3], v[36:37]
	v_pk_mul_f32 v[34:35], v[0:1], v[38:39]
	v_pk_mul_f32 v[38:39], v[6:7], v[46:47]
	global_store_dwordx4 v[42:43], v[34:37], off sc1
	s_nop 1
	v_pk_mul_f32 v[36:37], v[4:5], v[40:41]
	v_lshlrev_b32_e32 v34, 16, v32
	v_and_b32_e32 v35, 0xffff0000, v32
	v_lshlrev_b32_e32 v32, 16, v33
	v_and_b32_e32 v33, 0xffff0000, v33
	global_store_dwordx4 v[42:43], v[36:39], off offset:1024 sc1
	v_pk_mul_f32 v[32:33], v[44:45], v[32:33] op_sel_hi:[0,1]
	s_nop 0
	v_pk_mul_f32 v[36:37], v[44:45], v[34:35] op_sel_hi:[0,1]
	v_pk_mul_f32 v[34:35], v[10:11], v[32:33]
	v_pk_mul_f32 v[32:33], v[8:9], v[36:37]
	global_store_dwordx4 v[42:43], v[32:35], off offset:2048 sc1
	s_nop 1
	v_lshlrev_b32_e32 v32, 16, v30
	v_and_b32_e32 v33, 0xffff0000, v30
	v_lshlrev_b32_e32 v30, 16, v31
	v_and_b32_e32 v31, 0xffff0000, v31
	v_pk_mul_f32 v[34:35], v[44:45], v[32:33] op_sel_hi:[0,1]
	v_pk_mul_f32 v[30:31], v[44:45], v[30:31] op_sel_hi:[0,1]
	v_pk_mul_f32 v[32:33], v[14:15], v[30:31]
	v_pk_mul_f32 v[30:31], v[12:13], v[34:35]
	global_store_dwordx4 v[42:43], v[30:33], off offset:3072 sc1
	s_andn2_b64 vcc, exec, s[8:9]
	s_cbranch_vccnz .LBB0_952
.LBB0_966:
	s_waitcnt vmcnt(4)
	ds_bpermute_b32 v30, v54, v61
	s_ashr_i32 s7, s6, 31
	s_lshl_b64 s[6:7], s[6:7], 12
	s_waitcnt lgkmcnt(0)
	v_add_f32_e32 v30, v61, v30
	ds_bpermute_b32 v31, v55, v30
	s_waitcnt lgkmcnt(0)
	v_add_f32_e32 v30, v30, v31
	ds_bpermute_b32 v31, v56, v30
	s_waitcnt lgkmcnt(0)
	v_add_f32_e32 v32, v30, v31
	ds_bpermute_b32 v33, v57, v32
	v_lshlrev_b32_e32 v30, 16, v28
	v_and_b32_e32 v31, 0xffff0000, v28
	s_waitcnt lgkmcnt(0)
	v_add_f32_e32 v28, v32, v33
	ds_bpermute_b32 v34, v58, v28
	v_lshlrev_b32_e32 v32, 16, v26
	v_and_b32_e32 v33, 0xffff0000, v26
	v_lshlrev_b32_e32 v28, 16, v29
	v_and_b32_e32 v29, 0xffff0000, v29
	s_waitcnt lgkmcnt(0)
	v_fmamk_f32 v26, v34, 0x3a800000, v59
	v_mul_f32_e32 v34, 0x4f800000, v26
	v_cmp_gt_f32_e32 vcc, s21, v26
	s_nop 1
	v_cndmask_b32_e32 v34, v26, v34, vcc
	v_sqrt_f32_e32 v35, v34
	v_lshlrev_b32_e32 v26, 16, v27
	v_and_b32_e32 v27, 0xffff0000, v27
	v_add_u32_e32 v36, -1, v35
	v_add_u32_e32 v37, 1, v35
	v_fma_f32 v38, -v36, v35, v34
	v_fma_f32 v39, -v37, v35, v34
	v_cmp_ge_f32_e64 s[2:3], 0, v38
	s_nop 1
	v_cndmask_b32_e64 v35, v35, v36, s[2:3]
	v_cmp_lt_f32_e64 s[2:3], 0, v39
	s_nop 1
	v_cndmask_b32_e64 v35, v35, v37, s[2:3]
	v_mul_f32_e32 v36, 0x37800000, v35
	v_cndmask_b32_e32 v35, v35, v36, vcc
	v_cmp_class_f32_e32 vcc, v34, v60
	s_nop 1
	v_cndmask_b32_e32 v36, v35, v34, vcc
	v_div_scale_f32 v37, s[2:3], v36, v36, 1.0
	v_rcp_f32_e32 v38, v37
	v_div_scale_f32 v39, vcc, 1.0, v36, 1.0
	v_lshl_add_u64 v[34:35], v[20:21], 0, s[6:7]
	v_fma_f32 v40, -v37, v38, 1.0
	v_fmac_f32_e32 v38, v40, v38
	v_mul_f32_e32 v40, v39, v38
	v_fma_f32 v41, -v37, v40, v39
	v_fmac_f32_e32 v40, v41, v38
	v_fma_f32 v37, -v37, v40, v39
	v_div_fmas_f32 v37, v37, v38, v40
	v_div_fixup_f32 v36, v37, v36, 1.0
	v_pk_mul_f32 v[30:31], v[36:37], v[30:31] op_sel_hi:[0,1]
	v_pk_mul_f32 v[28:29], v[36:37], v[28:29] op_sel_hi:[0,1]
	v_pk_mul_f32 v[32:33], v[36:37], v[32:33] op_sel_hi:[0,1]
	v_pk_mul_f32 v[38:39], v[36:37], v[26:27] op_sel_hi:[0,1]
	v_pk_mul_f32 v[28:29], v[2:3], v[28:29]
	v_pk_mul_f32 v[26:27], v[0:1], v[30:31]
	v_pk_mul_f32 v[30:31], v[6:7], v[38:39]
	global_store_dwordx4 v[34:35], v[26:29], off sc1
	s_nop 1
	v_pk_mul_f32 v[28:29], v[4:5], v[32:33]
	v_lshlrev_b32_e32 v26, 16, v24
	v_and_b32_e32 v27, 0xffff0000, v24
	v_lshlrev_b32_e32 v24, 16, v25
	v_and_b32_e32 v25, 0xffff0000, v25
	global_store_dwordx4 v[34:35], v[28:31], off offset:1024 sc1
	v_pk_mul_f32 v[24:25], v[36:37], v[24:25] op_sel_hi:[0,1]
	s_nop 0
	v_pk_mul_f32 v[28:29], v[36:37], v[26:27] op_sel_hi:[0,1]
	v_pk_mul_f32 v[26:27], v[10:11], v[24:25]
	v_pk_mul_f32 v[24:25], v[8:9], v[28:29]
	global_store_dwordx4 v[34:35], v[24:27], off offset:2048 sc1
	s_nop 1
	v_lshlrev_b32_e32 v24, 16, v22
	v_and_b32_e32 v25, 0xffff0000, v22
	v_lshlrev_b32_e32 v22, 16, v23
	v_and_b32_e32 v23, 0xffff0000, v23
	v_pk_mul_f32 v[26:27], v[36:37], v[24:25] op_sel_hi:[0,1]
	v_pk_mul_f32 v[22:23], v[36:37], v[22:23] op_sel_hi:[0,1]
	v_pk_mul_f32 v[24:25], v[14:15], v[22:23]
	v_pk_mul_f32 v[22:23], v[12:13], v[26:27]
	global_store_dwordx4 v[34:35], v[22:25], off offset:3072 sc1
	s_branch .LBB0_952
